# P1 f32 K/V output stores with sc1 (write-through, not kept in L2); on top of v38
# baseline (speedup 1.0000x reference)
.LBB0_106:
	s_lshl_b32 s10, s10, 8
	s_and_b32 s10, s10, 0x700
	s_mul_hi_i32 s21, s11, 0x2100000
	s_mul_i32 s11, s11, 0x2100000
	v_or_b32_e32 v150, s10, v158
	s_add_u32 s10, s47, s11
	s_addc_u32 s11, s48, s21
	v_lshlrev_b32_e32 v138, 1, v150
	v_lshl_add_u64 v[154:155], s[10:11], 0, v[138:139]
	v_lshlrev_b64 v[174:175], 12, v[152:153]
	s_cmp_lg_u64 s[30:31], 0
	v_lshlrev_b32_e32 v138, 2, v150
	v_lshl_add_u64 v[178:179], v[154:155], 0, v[174:175]
	v_cvt_pk_bf16_f32 v174, v126, v127
	v_cvt_pk_bf16_f32 v175, v128, v129
	v_cvt_pk_bf16_f32 v176, v122, v123
	v_cvt_pk_bf16_f32 v177, v124, v125
	s_cselect_b64 s[28:29], -1, 0
	s_cmp_eq_u64 s[30:31], 0
	v_lshl_add_u64 v[150:151], s[30:31], 0, v[138:139]
	global_store_dwordx4 v[178:179], v[174:177], off
	s_nop 1
	v_cvt_pk_bf16_f32 v174, v118, v119
	v_cvt_pk_bf16_f32 v175, v120, v121
	v_cvt_pk_bf16_f32 v176, v114, v115
	v_cvt_pk_bf16_f32 v177, v116, v117
	global_store_dwordx4 v[178:179], v[174:177], off offset:256
	s_cbranch_scc1 .LBB0_108
	s_nop 0
	v_lshlrev_b64 v[174:175], 13, v[152:153]
	v_lshl_add_u64 v[174:175], v[150:151], 0, v[174:175]
	global_store_dwordx4 v[174:175], v[126:129], off sc1
	global_store_dwordx4 v[174:175], v[122:125], off offset:16 sc1
	global_store_dwordx4 v[174:175], v[118:121], off offset:512 sc1
	global_store_dwordx4 v[174:175], v[114:117], off offset:528 sc1

.LBB0_110:
	v_lshlrev_b64 v[116:117], 12, v[114:115]
	v_lshl_add_u64 v[120:121], v[154:155], 0, v[116:117]
	v_cvt_pk_bf16_f32 v116, v110, v111
	v_cvt_pk_bf16_f32 v117, v112, v113
	v_cvt_pk_bf16_f32 v118, v106, v107
	v_cvt_pk_bf16_f32 v119, v108, v109
	v_cndmask_b32_e64 v122, 0, 1, s[28:29]
	global_store_dwordx4 v[120:121], v[116:119], off
	v_cmp_ne_u32_e64 s[10:11], 1, v122
	s_andn2_b64 vcc, exec, s[28:29]
	v_cvt_pk_bf16_f32 v116, v102, v103
	v_cvt_pk_bf16_f32 v117, v104, v105
	v_cvt_pk_bf16_f32 v118, v98, v99
	v_cvt_pk_bf16_f32 v119, v100, v101
	global_store_dwordx4 v[120:121], v[116:119], off offset:256
	s_cbranch_vccnz .LBB0_112
	v_lshlrev_b64 v[114:115], 13, v[114:115]
	v_lshl_add_u64 v[114:115], v[150:151], 0, v[114:115]
	global_store_dwordx4 v[114:115], v[110:113], off sc1
	global_store_dwordx4 v[114:115], v[106:109], off offset:16 sc1
	global_store_dwordx4 v[114:115], v[102:105], off offset:512 sc1
	global_store_dwordx4 v[114:115], v[98:101], off offset:528 sc1

.LBB0_114:
	v_lshlrev_b64 v[100:101], 12, v[98:99]
	v_lshl_add_u64 v[104:105], v[154:155], 0, v[100:101]
	v_cvt_pk_bf16_f32 v100, v94, v95
	v_cvt_pk_bf16_f32 v101, v96, v97
	v_cvt_pk_bf16_f32 v102, v90, v91
	v_cvt_pk_bf16_f32 v103, v92, v93
	global_store_dwordx4 v[104:105], v[100:103], off
	s_and_b64 vcc, exec, s[10:11]
	s_nop 0
	v_cvt_pk_bf16_f32 v100, v86, v87
	v_cvt_pk_bf16_f32 v101, v88, v89
	v_cvt_pk_bf16_f32 v102, v82, v83
	v_cvt_pk_bf16_f32 v103, v84, v85
	global_store_dwordx4 v[104:105], v[100:103], off offset:256
	s_cbranch_vccnz .LBB0_116
	v_lshlrev_b64 v[98:99], 13, v[98:99]
	v_lshl_add_u64 v[98:99], v[150:151], 0, v[98:99]
	global_store_dwordx4 v[98:99], v[94:97], off sc1
	global_store_dwordx4 v[98:99], v[90:93], off offset:16 sc1
	global_store_dwordx4 v[98:99], v[86:89], off offset:512 sc1
	global_store_dwordx4 v[98:99], v[82:85], off offset:528 sc1

.LBB0_118:
	v_lshlrev_b64 v[84:85], 12, v[82:83]
	v_lshl_add_u64 v[88:89], v[154:155], 0, v[84:85]
	v_cvt_pk_bf16_f32 v84, v78, v79
	v_cvt_pk_bf16_f32 v85, v80, v81
	v_cvt_pk_bf16_f32 v86, v74, v75
	v_cvt_pk_bf16_f32 v87, v76, v77
	global_store_dwordx4 v[88:89], v[84:87], off
	s_and_b64 vcc, exec, s[10:11]
	s_nop 0
	v_cvt_pk_bf16_f32 v84, v70, v71
	v_cvt_pk_bf16_f32 v85, v72, v73
	v_cvt_pk_bf16_f32 v86, v66, v67
	v_cvt_pk_bf16_f32 v87, v68, v69
	global_store_dwordx4 v[88:89], v[84:87], off offset:256
	s_cbranch_vccnz .LBB0_120
	v_lshlrev_b64 v[82:83], 13, v[82:83]
	v_lshl_add_u64 v[82:83], v[150:151], 0, v[82:83]
	global_store_dwordx4 v[82:83], v[78:81], off sc1
	global_store_dwordx4 v[82:83], v[74:77], off offset:16 sc1
	global_store_dwordx4 v[82:83], v[70:73], off offset:512 sc1
	global_store_dwordx4 v[82:83], v[66:69], off offset:528 sc1

.LBB0_122:
	v_lshlrev_b64 v[68:69], 12, v[66:67]
	v_lshl_add_u64 v[72:73], v[154:155], 0, v[68:69]
	v_cvt_pk_bf16_f32 v68, v62, v63
	v_cvt_pk_bf16_f32 v69, v64, v65
	v_cvt_pk_bf16_f32 v70, v58, v59
	v_cvt_pk_bf16_f32 v71, v60, v61
	global_store_dwordx4 v[72:73], v[68:71], off
	s_and_b64 vcc, exec, s[10:11]
	s_nop 0
	v_cvt_pk_bf16_f32 v68, v54, v55
	v_cvt_pk_bf16_f32 v69, v56, v57
	v_cvt_pk_bf16_f32 v70, v50, v51
	v_cvt_pk_bf16_f32 v71, v52, v53
	global_store_dwordx4 v[72:73], v[68:71], off offset:256
	s_cbranch_vccnz .LBB0_124
	v_lshlrev_b64 v[66:67], 13, v[66:67]
	v_lshl_add_u64 v[66:67], v[150:151], 0, v[66:67]
	global_store_dwordx4 v[66:67], v[62:65], off sc1
	global_store_dwordx4 v[66:67], v[58:61], off offset:16 sc1
	global_store_dwordx4 v[66:67], v[54:57], off offset:512 sc1
	global_store_dwordx4 v[66:67], v[50:53], off offset:528 sc1

.LBB0_126:
	v_lshlrev_b64 v[52:53], 12, v[50:51]
	v_lshl_add_u64 v[56:57], v[154:155], 0, v[52:53]
	v_cvt_pk_bf16_f32 v52, v46, v47
	v_cvt_pk_bf16_f32 v53, v48, v49
	v_cvt_pk_bf16_f32 v54, v42, v43
	v_cvt_pk_bf16_f32 v55, v44, v45
	global_store_dwordx4 v[56:57], v[52:55], off
	s_and_b64 vcc, exec, s[10:11]
	s_nop 0
	v_cvt_pk_bf16_f32 v52, v38, v39
	v_cvt_pk_bf16_f32 v53, v40, v41
	v_cvt_pk_bf16_f32 v54, v34, v35
	v_cvt_pk_bf16_f32 v55, v36, v37
	global_store_dwordx4 v[56:57], v[52:55], off offset:256
	s_cbranch_vccnz .LBB0_128
	v_lshlrev_b64 v[50:51], 13, v[50:51]
	v_lshl_add_u64 v[50:51], v[150:151], 0, v[50:51]
	global_store_dwordx4 v[50:51], v[46:49], off sc1
	global_store_dwordx4 v[50:51], v[42:45], off offset:16 sc1
	global_store_dwordx4 v[50:51], v[38:41], off offset:512 sc1
	global_store_dwordx4 v[50:51], v[34:37], off offset:528 sc1

.LBB0_130:
	v_lshlrev_b64 v[36:37], 12, v[34:35]
	v_lshl_add_u64 v[40:41], v[154:155], 0, v[36:37]
	v_cvt_pk_bf16_f32 v36, v30, v31
	v_cvt_pk_bf16_f32 v37, v32, v33
	v_cvt_pk_bf16_f32 v38, v26, v27
	v_cvt_pk_bf16_f32 v39, v28, v29
	global_store_dwordx4 v[40:41], v[36:39], off
	s_and_b64 vcc, exec, s[10:11]
	s_nop 0
	v_cvt_pk_bf16_f32 v36, v22, v23
	v_cvt_pk_bf16_f32 v37, v24, v25
	v_cvt_pk_bf16_f32 v38, v18, v19
	v_cvt_pk_bf16_f32 v39, v20, v21
	global_store_dwordx4 v[40:41], v[36:39], off offset:256
	s_cbranch_vccnz .LBB0_132
	v_lshlrev_b64 v[34:35], 13, v[34:35]
	v_lshl_add_u64 v[34:35], v[150:151], 0, v[34:35]
	global_store_dwordx4 v[34:35], v[30:33], off sc1
	global_store_dwordx4 v[34:35], v[26:29], off offset:16 sc1
	global_store_dwordx4 v[34:35], v[22:25], off offset:512 sc1
	global_store_dwordx4 v[34:35], v[18:21], off offset:528 sc1

.LBB0_134:
	v_lshlrev_b64 v[20:21], 12, v[18:19]
	v_lshl_add_u64 v[24:25], v[154:155], 0, v[20:21]
	v_cvt_pk_bf16_f32 v20, v14, v15
	v_cvt_pk_bf16_f32 v21, v16, v17
	v_cvt_pk_bf16_f32 v22, v10, v11
	v_cvt_pk_bf16_f32 v23, v12, v13
	global_store_dwordx4 v[24:25], v[20:23], off
	s_and_b64 vcc, exec, s[10:11]
	s_nop 0
	v_cvt_pk_bf16_f32 v20, v6, v7
	v_cvt_pk_bf16_f32 v21, v8, v9
	v_cvt_pk_bf16_f32 v22, v2, v3
	v_cvt_pk_bf16_f32 v23, v4, v5
	global_store_dwordx4 v[24:25], v[20:23], off offset:256
	s_cbranch_vccnz .LBB0_136
	v_lshlrev_b64 v[18:19], 13, v[18:19]
	v_lshl_add_u64 v[18:19], v[150:151], 0, v[18:19]
	global_store_dwordx4 v[18:19], v[14:17], off sc1
	global_store_dwordx4 v[18:19], v[10:13], off offset:16 sc1
	global_store_dwordx4 v[18:19], v[6:9], off offset:512 sc1
	global_store_dwordx4 v[18:19], v[2:5], off offset:528 sc1
